# GU K-loop: one extra LDS-DMA per wave per K-iter streams next layer's f32 gate|up weights toward cache ahead of the conversion tail (vmcnt 8->9 on two waits)
# baseline (speedup 1.0000x reference)
; #define PG8_STAGE(bufoff, gbase, voff) do { _Pragma("unroll") for (int _i = 0; _i < 2; ++_i) \
;         __builtin_amdgcn_global_load_lds((const unsigned*)((const char*)(gbase) + (voff)[_i]), (LAS unsigned*)(lds + (bufoff) + ldsw + _i * 8192), 16, 0, 0); } while (0)
; #define PG8_LDA(dst, b, h) do { _Pragma("unroll") for (int m = 0; m < 4; ++m) _Pragma("unroll") for (int k = 0; k < 2; ++k) dst[m][k] = *(const LAS bf16x8*)(lds + PG8_SA(b, h) + aoff + m * 2048 + k * 1024); } while (0)
; #define PG8_LDB(dst, b, h) do { _Pragma("unroll") for (int n = 0; n < 2; ++n) _Pragma("unroll") for (int k = 0; k < 2; ++k) dst[n][k] = *(const LAS bf16x8*)(lds + PG8_SB(b, h) + boff + n * 2048 + k * 1024); } while (0)
; #define PG8_MMA(ai, bj, At, Bt) do { __builtin_amdgcn_s_setprio(1); _Pragma("unroll") for (int m = 0; m < 4; ++m) _Pragma("unroll") for (int n = 0; n < 2; ++n) _Pragma("unroll") for (int k = 0; k < 2; ++k) \
;         acc[ai][bj][m][n] = __builtin_amdgcn_mfma_f32_16x16x32_bf16(Bt[n][k], At[m][k], acc[ai][bj][m][n], 0, 0, 0); __builtin_amdgcn_s_setprio(0); } while (0)
; #define PG8_WAIT_V(n) asm volatile("s_waitcnt vmcnt(" #n ")" ::: "memory")
; #define PG8_WAIT_L(n) asm volatile("s_waitcnt lgkmcnt(" #n ")" ::: "memory")
; #define PG8_BAR __builtin_amdgcn_s_barrier()
; #define PG8_SCHED __builtin_amdgcn_sched_barrier(0)
; template <class Epi, bool ALIGN_EPI>
; __device__ __forceinline__ void gemm_phase(LAS unsigned char* lds, const Gemm g, int G, int cid, const Epi& E) {
;     ...
;     f32x4 acc[2][2][4][2];
; #pragma unroll
;     for (int a = 0; a < 2; ++a)
; #pragma unroll
;         for (int b = 0; b < 2; ++b)
; #pragma unroll
;             for (int m = 0; m < 4; ++m)
; #pragma unroll
;                 for (int n = 0; n < 2; ++n) acc[a][b][m][n] = (f32x4){0.f, 0.f, 0.f, 0.f};
;     ...
;             const char* a1 = cA + (size_t)(t + 1) * kA;
;             const char* a2 = last ? nA : cA + (size_t)(t + 2) * kA; const char* b2 = last ? nB : cB + (size_t)(t + 2) * kB;
;             const char* a3 = a2 + kA; const char* b3 = b2 + kB;
;             PG8_LDB(B0, 0, 0); PG8_LDB(B1, 0, 1); PG8_SCHED; PG8_LDA(At, 0, 0); PG8_STAGE(PG8_SA(1, 1), a1 + hA, voffA);
;             PG8_WAIT_V(8); PG8_WAIT_L(0); PG8_BAR; PG8_MMA(0, 0, At, B0); PG8_MMA(0, 1, At, B1); PG8_BAR; PG8_SCHED;
.LBB0_812:
	s_and_b32 s6, s78, 0x7fffffff
	s_mov_b32 s7, s31
	s_lshl_b64 s[6:7], s[6:7], 14
	s_add_u32 s46, s0, s6
	s_addc_u32 s47, s1, s7
	s_and_b64 s[6:7], s[42:43], exec
	s_cselect_b32 s49, s47, s51
	s_cselect_b32 s48, s46, s50
	s_add_u32 s50, s50, 0x2c0000
	v_mov_b32_e32 v0, 0
	s_addc_u32 s51, s51, 0
	s_mov_b32 s91, -2
	v_mov_b32_e32 v1, v0
	v_mov_b32_e32 v2, v0
	v_mov_b32_e32 v3, v0
	v_mov_b32_e32 v4, v0
	v_mov_b32_e32 v5, v0
	v_mov_b32_e32 v6, v0
	v_mov_b32_e32 v7, v0
	v_mov_b32_e32 v16, v0
	v_mov_b32_e32 v17, v0
	v_mov_b32_e32 v18, v0
	v_mov_b32_e32 v19, v0
	v_mov_b32_e32 v20, v0
	v_mov_b32_e32 v21, v0
	v_mov_b32_e32 v22, v0
	v_mov_b32_e32 v23, v0
	v_mov_b32_e32 v32, v0
	v_mov_b32_e32 v33, v0
	v_mov_b32_e32 v34, v0
	v_mov_b32_e32 v35, v0
	v_mov_b32_e32 v36, v0
	v_mov_b32_e32 v37, v0
	v_mov_b32_e32 v38, v0
	v_mov_b32_e32 v39, v0
	v_mov_b32_e32 v48, v0
	v_mov_b32_e32 v49, v0
	v_mov_b32_e32 v50, v0
	v_mov_b32_e32 v51, v0
	v_mov_b32_e32 v52, v0
	v_mov_b32_e32 v53, v0
	v_mov_b32_e32 v54, v0
	v_mov_b32_e32 v55, v0
	v_mov_b32_e32 v8, v0
	v_mov_b32_e32 v9, v0
	v_mov_b32_e32 v10, v0
	v_mov_b32_e32 v11, v0
	v_mov_b32_e32 v12, v0
	v_mov_b32_e32 v13, v0
	v_mov_b32_e32 v14, v0
	v_mov_b32_e32 v15, v0
	v_mov_b32_e32 v24, v0
	v_mov_b32_e32 v25, v0
	v_mov_b32_e32 v26, v0
	v_mov_b32_e32 v27, v0
	v_mov_b32_e32 v28, v0
	v_mov_b32_e32 v29, v0
	v_mov_b32_e32 v30, v0
	v_mov_b32_e32 v31, v0
	v_mov_b32_e32 v40, v0
	v_mov_b32_e32 v41, v0
	v_mov_b32_e32 v42, v0
	v_mov_b32_e32 v43, v0
	v_mov_b32_e32 v44, v0
	v_mov_b32_e32 v45, v0
	v_mov_b32_e32 v46, v0
	v_mov_b32_e32 v47, v0
	v_mov_b32_e32 v56, v0
	v_mov_b32_e32 v57, v0
	v_mov_b32_e32 v58, v0
	v_mov_b32_e32 v59, v0
	v_mov_b32_e32 v60, v0
	v_mov_b32_e32 v61, v0
	v_mov_b32_e32 v62, v0
	v_mov_b32_e32 v63, v0
	v_mov_b32_e32 v64, v0
	v_mov_b32_e32 v65, v0
	v_mov_b32_e32 v66, v0
	v_mov_b32_e32 v67, v0
	v_mov_b32_e32 v68, v0
	v_mov_b32_e32 v69, v0
	v_mov_b32_e32 v70, v0
	v_mov_b32_e32 v71, v0
	v_mov_b32_e32 v80, v0
	v_mov_b32_e32 v81, v0
	v_mov_b32_e32 v82, v0
	v_mov_b32_e32 v83, v0
	v_mov_b32_e32 v84, v0
	v_mov_b32_e32 v85, v0
	v_mov_b32_e32 v86, v0
	v_mov_b32_e32 v87, v0
	v_mov_b32_e32 v96, v0
	v_mov_b32_e32 v97, v0
	v_mov_b32_e32 v98, v0
	v_mov_b32_e32 v99, v0
	v_mov_b32_e32 v100, v0
	v_mov_b32_e32 v101, v0
	v_mov_b32_e32 v102, v0
	v_mov_b32_e32 v103, v0
	v_mov_b32_e32 v112, v0
	v_mov_b32_e32 v113, v0
	v_mov_b32_e32 v114, v0
	v_mov_b32_e32 v115, v0
	v_mov_b32_e32 v116, v0
	v_mov_b32_e32 v117, v0
	v_mov_b32_e32 v118, v0
	v_mov_b32_e32 v119, v0
	v_mov_b32_e32 v72, v0
	v_mov_b32_e32 v73, v0
	v_mov_b32_e32 v74, v0
	v_mov_b32_e32 v75, v0
	v_mov_b32_e32 v76, v0
	v_mov_b32_e32 v77, v0
	v_mov_b32_e32 v78, v0
	v_mov_b32_e32 v79, v0
	v_mov_b32_e32 v88, v0
	v_mov_b32_e32 v89, v0
	v_mov_b32_e32 v90, v0
	v_mov_b32_e32 v91, v0
	v_mov_b32_e32 v92, v0
	v_mov_b32_e32 v93, v0
	v_mov_b32_e32 v94, v0
	v_mov_b32_e32 v95, v0
	v_mov_b32_e32 v104, v0
	v_mov_b32_e32 v105, v0
	v_mov_b32_e32 v106, v0
	v_mov_b32_e32 v107, v0
	v_mov_b32_e32 v108, v0
	v_mov_b32_e32 v109, v0
	v_mov_b32_e32 v110, v0
	v_mov_b32_e32 v111, v0
	v_mov_b32_e32 v120, v0
	v_mov_b32_e32 v121, v0
	v_mov_b32_e32 v122, v0
	v_mov_b32_e32 v123, v0
	v_mov_b32_e32 v124, v0
	v_mov_b32_e32 v125, v0
	v_mov_b32_e32 v126, v0
	v_mov_b32_e32 v127, v0
	v_mbcnt_lo_u32_b32 v228, -1, 0
	v_mbcnt_hi_u32_b32 v228, -1, v228
	v_lshlrev_b32_e32 v228, 4, v228
	s_branch .LBB0_814
.LBB0_813:
	s_add_u32 s54, s52, 0x100
	s_addc_u32 s55, s53, 0
	s_and_b64 s[6:7], exec, s[58:59]
	s_cselect_b32 s59, s45, s55
	s_cselect_b32 s58, s44, s54
	s_add_i32 s6, 0, 0x10000
	s_add_i32 s92, 0, 0x14000
	v_add_u32_e32 v144, s6, v176
	v_add_u32_e32 v160, s92, v176
	ds_read_b128 v[128:131], v144
	ds_read_b128 v[132:135], v144 offset:1024
	ds_read_b128 v[140:143], v144 offset:2048
	ds_read_b128 v[144:147], v144 offset:3072
	ds_read_b128 v[148:151], v160
	ds_read_b128 v[152:155], v160 offset:1024
	ds_read_b128 v[156:159], v160 offset:2048
	ds_read_b128 v[160:163], v160 offset:3072
	v_lshl_add_u64 v[198:199], s[52:53], 0, v[170:171]
	s_add_i32 m0, s13, 0xc000
	ds_read_b128 v[180:183], v179
	ds_read_b128 v[184:187], v179 offset:1024
	ds_read_b128 v[188:191], v179 offset:2048
	ds_read_b128 v[206:209], v179 offset:3072
	ds_read_b128 v[210:213], v179 offset:4096
	ds_read_b128 v[214:217], v179 offset:5120
	ds_read_b128 v[218:221], v179 offset:6144
	ds_read_b128 v[222:225], v179 offset:7168
	global_load_lds_dwordx4 v[198:199], off
	v_lshl_add_u64 v[198:199], s[52:53], 0, v[172:173]
	s_add_i32 m0, s13, 0xe000
	s_nop 0
	global_load_lds_dwordx4 v[198:199], off
	s_add_i32 m0, s91, 2
	s_lshr_b32 m0, m0, 1
	s_lshl_b32 s7, s90, 4
	s_add_i32 m0, m0, s7
	s_sub_i32 m0, m0, 36
	s_cmp_lt_u32 m0, 44
	s_cselect_b32 m0, m0, 0
	s_cmp_lt_u32 s26, 3
	s_cselect_b32 m0, m0, 0
	v_readlane_b32 s7, v252, 10
	s_lshl_b32 s7, s7, 3
	s_lshr_b32 vcc_lo, s13, 10
	s_add_i32 s7, s7, vcc_lo
	s_mul_i32 s7, s7, 44
	s_add_i32 m0, m0, s7
	s_lshl_b32 m0, m0, 10
	s_add_i32 s7, s26, 1
	s_min_u32 s7, s7, 3
	s_mul_i32 s7, s7, 0x5800000
	s_add_u32 s7, s7, m0
	v_readlane_b32 vcc_lo, v252, 6
	v_readlane_b32 vcc_hi, v252, 7
	s_add_u32 vcc_lo, vcc_lo, s7
	s_addc_u32 vcc_hi, vcc_hi, 0
	s_mov_b32 m0, 0x22c00
	s_nop 1
	global_load_lds_dwordx4 v228, vcc
	s_waitcnt vmcnt(9)
	s_waitcnt lgkmcnt(0)
	s_barrier
; #define PG8_STAGE(bufoff, gbase, voff) do { _Pragma("unroll") for (int _i = 0; _i < 2; ++_i) \
;         __builtin_amdgcn_global_load_lds((const unsigned*)((const char*)(gbase) + (voff)[_i]), (LAS unsigned*)(lds + (bufoff) + ldsw + _i * 8192), 16, 0, 0); } while (0)
; #define PG8_LDA(dst, b, h) do { _Pragma("unroll") for (int m = 0; m < 4; ++m) _Pragma("unroll") for (int k = 0; k < 2; ++k) dst[m][k] = *(const LAS bf16x8*)(lds + PG8_SA(b, h) + aoff + m * 2048 + k * 1024); } while (0)
; #define PG8_MMA(ai, bj, At, Bt) do { __builtin_amdgcn_s_setprio(1); _Pragma("unroll") for (int m = 0; m < 4; ++m) _Pragma("unroll") for (int n = 0; n < 2; ++n) _Pragma("unroll") for (int k = 0; k < 2; ++k) \
;         acc[ai][bj][m][n] = __builtin_amdgcn_mfma_f32_16x16x32_bf16(Bt[n][k], At[m][k], acc[ai][bj][m][n], 0, 0, 0); __builtin_amdgcn_s_setprio(0); } while (0)
; #define PG8_WAIT_V(n) asm volatile("s_waitcnt vmcnt(" #n ")" ::: "memory")
; #define PG8_WAIT_L(n) asm volatile("s_waitcnt lgkmcnt(" #n ")" ::: "memory")
; #define PG8_BAR __builtin_amdgcn_s_barrier()
; #define PG8_SCHED __builtin_amdgcn_sched_barrier(0)
; template <class Epi, bool ALIGN_EPI>
; __device__ __forceinline__ void gemm_phase(LAS unsigned char* lds, const Gemm g, int G, int cid, const Epi& E) {
;     ...
;             PG8_WAIT_V(8); PG8_WAIT_L(0); PG8_BAR; PG8_MMA(0, 0, At, B0); PG8_MMA(0, 1, At, B1); PG8_BAR; PG8_SCHED;
;             PG8_LDA(At, 0, 1); PG8_STAGE(PG8_SB(0, 0), b2, voffB); PG8_STAGE(PG8_SB(0, 1), b2 + hB, voffB); PG8_STAGE(PG8_SA(0, 0), a2, voffA);
;             PG8_WAIT_V(8); PG8_WAIT_L(0); PG8_BAR; PG8_MMA(1, 0, At, B0); PG8_MMA(1, 1, At, B1); PG8_BAR; PG8_SCHED;
	s_setprio 1
	s_waitcnt lgkmcnt(0)
	v_mfma_f32_16x16x32_bf16 v[124:127], v[128:131], v[180:183], v[124:127]
	v_mfma_f32_16x16x32_bf16 v[120:123], v[140:143], v[180:183], v[120:123]
	v_mfma_f32_16x16x32_bf16 v[108:111], v[128:131], v[188:191], v[108:111]
	v_mfma_f32_16x16x32_bf16 v[104:107], v[140:143], v[188:191], v[104:107]
	v_mfma_f32_16x16x32_bf16 v[92:95], v[128:131], v[210:213], v[92:95]
	v_mfma_f32_16x16x32_bf16 v[88:91], v[140:143], v[210:213], v[88:91]
	v_mfma_f32_16x16x32_bf16 v[76:79], v[128:131], v[218:221], v[76:79]
	v_mfma_f32_16x16x32_bf16 v[72:75], v[140:143], v[218:221], v[72:75]
	v_mfma_f32_16x16x32_bf16 v[124:127], v[132:135], v[184:187], v[124:127]
	v_mfma_f32_16x16x32_bf16 v[120:123], v[144:147], v[184:187], v[120:123]
	v_mfma_f32_16x16x32_bf16 v[108:111], v[132:135], v[206:209], v[108:111]
	v_mfma_f32_16x16x32_bf16 v[104:107], v[144:147], v[206:209], v[104:107]
	v_mfma_f32_16x16x32_bf16 v[92:95], v[132:135], v[214:217], v[92:95]
	v_mfma_f32_16x16x32_bf16 v[88:91], v[144:147], v[214:217], v[88:91]
	v_mfma_f32_16x16x32_bf16 v[76:79], v[132:135], v[222:225], v[76:79]
	v_mfma_f32_16x16x32_bf16 v[72:75], v[144:147], v[222:225], v[72:75]
	s_setprio 0
	s_setprio 1
	v_mfma_f32_16x16x32_bf16 v[116:119], v[148:151], v[180:183], v[116:119]
	v_mfma_f32_16x16x32_bf16 v[112:115], v[156:159], v[180:183], v[112:115]
	v_mfma_f32_16x16x32_bf16 v[100:103], v[148:151], v[188:191], v[100:103]
	v_mfma_f32_16x16x32_bf16 v[96:99], v[156:159], v[188:191], v[96:99]
	v_mfma_f32_16x16x32_bf16 v[84:87], v[148:151], v[210:213], v[84:87]
	v_mfma_f32_16x16x32_bf16 v[80:83], v[156:159], v[210:213], v[80:83]
	v_mfma_f32_16x16x32_bf16 v[68:71], v[148:151], v[218:221], v[68:71]
	v_mfma_f32_16x16x32_bf16 v[64:67], v[156:159], v[218:221], v[64:67]
	v_mfma_f32_16x16x32_bf16 v[116:119], v[152:155], v[184:187], v[116:119]
	v_mfma_f32_16x16x32_bf16 v[112:115], v[160:163], v[184:187], v[112:115]
	v_mfma_f32_16x16x32_bf16 v[100:103], v[152:155], v[206:209], v[100:103]
	v_mfma_f32_16x16x32_bf16 v[96:99], v[160:163], v[206:209], v[96:99]
	v_mfma_f32_16x16x32_bf16 v[84:87], v[152:155], v[214:217], v[84:87]
	v_mfma_f32_16x16x32_bf16 v[80:83], v[160:163], v[214:217], v[80:83]
	v_mfma_f32_16x16x32_bf16 v[68:71], v[152:155], v[222:225], v[68:71]
	v_mfma_f32_16x16x32_bf16 v[64:67], v[160:163], v[222:225], v[64:67]
	s_setprio 0
	s_barrier
	s_add_i32 s6, s6, s12
	v_lshl_add_u64 v[198:199], s[56:57], 0, v[164:165]
	s_mov_b32 m0, s6
	ds_read_b128 v[180:183], v179 offset:16384
	ds_read_b128 v[184:187], v179 offset:17408
	ds_read_b128 v[188:191], v179 offset:18432
	ds_read_b128 v[206:209], v179 offset:19456
	ds_read_b128 v[210:213], v179 offset:20480
	ds_read_b128 v[214:217], v179 offset:21504
	ds_read_b128 v[218:221], v179 offset:22528
	ds_read_b128 v[222:225], v179 offset:23552
	global_load_lds_dwordx4 v[198:199], off
	s_add_i32 m0, s6, 0x2000
	s_add_u32 s6, s56, 0x2000
	v_lshl_add_u64 v[198:199], s[56:57], 0, v[168:169]
	s_addc_u32 s7, s57, 0
	s_add_i32 s52, s92, s12
	global_load_lds_dwordx4 v[198:199], off
	v_lshl_add_u64 v[198:199], s[6:7], 0, v[164:165]
	s_mov_b32 m0, s52
	v_lshl_add_u64 v[200:201], s[58:59], 0, v[166:167]
	global_load_lds_dwordx4 v[198:199], off
	v_lshl_add_u64 v[198:199], s[6:7], 0, v[168:169]
	s_add_i32 m0, s52, 0x2000
	s_nop 0
	global_load_lds_dwordx4 v[198:199], off
	v_lshl_add_u64 v[198:199], s[58:59], 0, v[136:137]
	s_mov_b32 m0, s13
	s_nop 0
	global_load_lds_dwordx4 v[198:199], off
	s_mov_b32 m0, s24
	s_nop 0
	global_load_lds_dwordx4 v[200:201], off
	s_waitcnt vmcnt(9)
	s_waitcnt lgkmcnt(0)
	s_barrier
	s_setprio 1
	s_waitcnt lgkmcnt(0)
	v_mfma_f32_16x16x32_bf16 v[60:63], v[128:131], v[180:183], v[60:63]
	v_mfma_f32_16x16x32_bf16 v[56:59], v[140:143], v[180:183], v[56:59]
	v_mfma_f32_16x16x32_bf16 v[44:47], v[128:131], v[188:191], v[44:47]
	v_mfma_f32_16x16x32_bf16 v[40:43], v[140:143], v[188:191], v[40:43]
	v_mfma_f32_16x16x32_bf16 v[28:31], v[128:131], v[210:213], v[28:31]
	v_mfma_f32_16x16x32_bf16 v[24:27], v[140:143], v[210:213], v[24:27]
	v_mfma_f32_16x16x32_bf16 v[12:15], v[128:131], v[218:221], v[12:15]
	v_mfma_f32_16x16x32_bf16 v[8:11], v[140:143], v[218:221], v[8:11]
	v_mfma_f32_16x16x32_bf16 v[60:63], v[132:135], v[184:187], v[60:63]
	v_mfma_f32_16x16x32_bf16 v[56:59], v[144:147], v[184:187], v[56:59]
	v_mfma_f32_16x16x32_bf16 v[44:47], v[132:135], v[206:209], v[44:47]
	v_mfma_f32_16x16x32_bf16 v[40:43], v[144:147], v[206:209], v[40:43]
	v_mfma_f32_16x16x32_bf16 v[28:31], v[132:135], v[214:217], v[28:31]
	v_mfma_f32_16x16x32_bf16 v[24:27], v[144:147], v[214:217], v[24:27]
	v_mfma_f32_16x16x32_bf16 v[12:15], v[132:135], v[222:225], v[12:15]
	v_mfma_f32_16x16x32_bf16 v[8:11], v[144:147], v[222:225], v[8:11]
	s_setprio 0
	s_setprio 1
	v_mfma_f32_16x16x32_bf16 v[52:55], v[148:151], v[180:183], v[52:55]
	v_mfma_f32_16x16x32_bf16 v[48:51], v[156:159], v[180:183], v[48:51]
	v_mfma_f32_16x16x32_bf16 v[36:39], v[148:151], v[188:191], v[36:39]
	v_mfma_f32_16x16x32_bf16 v[32:35], v[156:159], v[188:191], v[32:35]
	v_mfma_f32_16x16x32_bf16 v[20:23], v[148:151], v[210:213], v[20:23]
	v_mfma_f32_16x16x32_bf16 v[16:19], v[156:159], v[210:213], v[16:19]
	v_mfma_f32_16x16x32_bf16 v[4:7], v[148:151], v[218:221], v[4:7]
	v_mfma_f32_16x16x32_bf16 v[0:3], v[156:159], v[218:221], v[0:3]
	v_mfma_f32_16x16x32_bf16 v[52:55], v[152:155], v[184:187], v[52:55]
	v_mfma_f32_16x16x32_bf16 v[48:51], v[160:163], v[184:187], v[48:51]
	v_mfma_f32_16x16x32_bf16 v[36:39], v[152:155], v[206:209], v[36:39]
	v_mfma_f32_16x16x32_bf16 v[32:35], v[160:163], v[206:209], v[32:35]
	v_mfma_f32_16x16x32_bf16 v[20:23], v[152:155], v[214:217], v[20:23]
	v_mfma_f32_16x16x32_bf16 v[16:19], v[160:163], v[214:217], v[16:19]
	v_mfma_f32_16x16x32_bf16 v[4:7], v[152:155], v[222:225], v[4:7]
	v_mfma_f32_16x16x32_bf16 v[0:3], v[160:163], v[222:225], v[0:3]
	s_setprio 0
	s_barrier
; #define PG8_STAGE(bufoff, gbase, voff) do { _Pragma("unroll") for (int _i = 0; _i < 2; ++_i) \
;         __builtin_amdgcn_global_load_lds((const unsigned*)((const char*)(gbase) + (voff)[_i]), (LAS unsigned*)(lds + (bufoff) + ldsw + _i * 8192), 16, 0, 0); } while (0)
; #define PG8_LDA(dst, b, h) do { _Pragma("unroll") for (int m = 0; m < 4; ++m) _Pragma("unroll") for (int k = 0; k < 2; ++k) dst[m][k] = *(const LAS bf16x8*)(lds + PG8_SA(b, h) + aoff + m * 2048 + k * 1024); } while (0)
; #define PG8_LDB(dst, b, h) do { _Pragma("unroll") for (int n = 0; n < 2; ++n) _Pragma("unroll") for (int k = 0; k < 2; ++k) dst[n][k] = *(const LAS bf16x8*)(lds + PG8_SB(b, h) + boff + n * 2048 + k * 1024); } while (0)
; #define PG8_MMA(ai, bj, At, Bt) do { __builtin_amdgcn_s_setprio(1); _Pragma("unroll") for (int m = 0; m < 4; ++m) _Pragma("unroll") for (int n = 0; n < 2; ++n) _Pragma("unroll") for (int k = 0; k < 2; ++k) \
;         acc[ai][bj][m][n] = __builtin_amdgcn_mfma_f32_16x16x32_bf16(Bt[n][k], At[m][k], acc[ai][bj][m][n], 0, 0, 0); __builtin_amdgcn_s_setprio(0); } while (0)
; #define PG8_WAIT_V(n) asm volatile("s_waitcnt vmcnt(" #n ")" ::: "memory")
; #define PG8_WAIT_L(n) asm volatile("s_waitcnt lgkmcnt(" #n ")" ::: "memory")
; #define PG8_BAR __builtin_amdgcn_s_barrier()
; #define PG8_SCHED __builtin_amdgcn_sched_barrier(0)
; template <class Epi, bool ALIGN_EPI>
; __device__ __forceinline__ void gemm_phase(LAS unsigned char* lds, const Gemm g, int G, int cid, const Epi& E) {
;     ...
;             PG8_WAIT_V(8); PG8_WAIT_L(0); PG8_BAR; PG8_MMA(1, 0, At, B0); PG8_MMA(1, 1, At, B1); PG8_BAR; PG8_SCHED;
;             PG8_LDB(B0, 1, 0); PG8_LDB(B1, 1, 1); PG8_SCHED; PG8_LDA(At, 1, 0); PG8_STAGE(PG8_SA(0, 1), a2 + hA, voffA);
;             PG8_WAIT_V(8); PG8_WAIT_L(0); PG8_BAR; PG8_MMA(0, 0, At, B0); PG8_MMA(0, 1, At, B1); PG8_BAR; PG8_SCHED;
	s_add_i32 s52, 0, 0x18000
	s_add_i32 s53, 0, 0x1c000
	v_add_u32_e32 v144, s52, v176
	v_add_u32_e32 v160, s53, v176
	ds_read_b128 v[128:131], v144
	ds_read_b128 v[132:135], v144 offset:1024
	ds_read_b128 v[140:143], v144 offset:2048
	ds_read_b128 v[144:147], v144 offset:3072
	ds_read_b128 v[148:151], v160
	ds_read_b128 v[152:155], v160 offset:1024
	ds_read_b128 v[156:159], v160 offset:2048
	ds_read_b128 v[160:163], v160 offset:3072
	s_add_u32 s6, s58, 0x84000
	s_addc_u32 s7, s59, 0
	s_mov_b32 m0, s25
	v_lshl_add_u64 v[226:227], s[6:7], 0, v[136:137]
	ds_read_b128 v[180:183], v179 offset:32768
	ds_read_b128 v[184:187], v179 offset:33792
	ds_read_b128 v[188:191], v179 offset:34816
	ds_read_b128 v[206:209], v179 offset:35840
	ds_read_b128 v[210:213], v179 offset:36864
	ds_read_b128 v[214:217], v179 offset:37888
	ds_read_b128 v[218:221], v179 offset:38912
	ds_read_b128 v[222:225], v179 offset:39936
	global_load_lds_dwordx4 v[226:227], off
	v_lshl_add_u64 v[226:227], s[6:7], 0, v[166:167]
	s_mov_b32 m0, s74
	s_nop 0
	global_load_lds_dwordx4 v[226:227], off
	s_waitcnt vmcnt(8)
	s_waitcnt lgkmcnt(0)
	s_barrier
	s_setprio 1
	s_waitcnt lgkmcnt(0)
	v_mfma_f32_16x16x32_bf16 v[124:127], v[128:131], v[180:183], v[124:127]
	v_mfma_f32_16x16x32_bf16 v[120:123], v[140:143], v[180:183], v[120:123]
	v_mfma_f32_16x16x32_bf16 v[108:111], v[128:131], v[188:191], v[108:111]
	v_mfma_f32_16x16x32_bf16 v[104:107], v[140:143], v[188:191], v[104:107]
	v_mfma_f32_16x16x32_bf16 v[92:95], v[128:131], v[210:213], v[92:95]
	v_mfma_f32_16x16x32_bf16 v[88:91], v[140:143], v[210:213], v[88:91]
	v_mfma_f32_16x16x32_bf16 v[76:79], v[128:131], v[218:221], v[76:79]
	v_mfma_f32_16x16x32_bf16 v[72:75], v[140:143], v[218:221], v[72:75]
	v_mfma_f32_16x16x32_bf16 v[124:127], v[132:135], v[184:187], v[124:127]
	v_mfma_f32_16x16x32_bf16 v[120:123], v[144:147], v[184:187], v[120:123]
	v_mfma_f32_16x16x32_bf16 v[108:111], v[132:135], v[206:209], v[108:111]
	v_mfma_f32_16x16x32_bf16 v[104:107], v[144:147], v[206:209], v[104:107]
	v_mfma_f32_16x16x32_bf16 v[92:95], v[132:135], v[214:217], v[92:95]
	v_mfma_f32_16x16x32_bf16 v[88:91], v[144:147], v[214:217], v[88:91]
	v_mfma_f32_16x16x32_bf16 v[76:79], v[132:135], v[222:225], v[76:79]
	v_mfma_f32_16x16x32_bf16 v[72:75], v[144:147], v[222:225], v[72:75]
	s_setprio 0
	s_setprio 1
	v_mfma_f32_16x16x32_bf16 v[116:119], v[148:151], v[180:183], v[116:119]
	v_mfma_f32_16x16x32_bf16 v[112:115], v[156:159], v[180:183], v[112:115]
	v_mfma_f32_16x16x32_bf16 v[100:103], v[148:151], v[188:191], v[100:103]
	v_mfma_f32_16x16x32_bf16 v[96:99], v[156:159], v[188:191], v[96:99]
	v_mfma_f32_16x16x32_bf16 v[84:87], v[148:151], v[210:213], v[84:87]
	v_mfma_f32_16x16x32_bf16 v[80:83], v[156:159], v[210:213], v[80:83]
	v_mfma_f32_16x16x32_bf16 v[68:71], v[148:151], v[218:221], v[68:71]
	v_mfma_f32_16x16x32_bf16 v[64:67], v[156:159], v[218:221], v[64:67]
	v_mfma_f32_16x16x32_bf16 v[116:119], v[152:155], v[184:187], v[116:119]
	v_mfma_f32_16x16x32_bf16 v[112:115], v[160:163], v[184:187], v[112:115]
	v_mfma_f32_16x16x32_bf16 v[100:103], v[152:155], v[206:209], v[100:103]
	v_mfma_f32_16x16x32_bf16 v[96:99], v[160:163], v[206:209], v[96:99]
	v_mfma_f32_16x16x32_bf16 v[84:87], v[152:155], v[214:217], v[84:87]
	v_mfma_f32_16x16x32_bf16 v[80:83], v[160:163], v[214:217], v[80:83]
	v_mfma_f32_16x16x32_bf16 v[68:71], v[152:155], v[222:225], v[68:71]
	v_mfma_f32_16x16x32_bf16 v[64:67], v[160:163], v[222:225], v[64:67]
	s_setprio 0
	s_barrier
; #define PG8_STAGE(bufoff, gbase, voff) do { _Pragma("unroll") for (int _i = 0; _i < 2; ++_i) \
;         __builtin_amdgcn_global_load_lds((const unsigned*)((const char*)(gbase) + (voff)[_i]), (LAS unsigned*)(lds + (bufoff) + ldsw + _i * 8192), 16, 0, 0); } while (0)
; #define PG8_LDA(dst, b, h) do { _Pragma("unroll") for (int m = 0; m < 4; ++m) _Pragma("unroll") for (int k = 0; k < 2; ++k) dst[m][k] = *(const LAS bf16x8*)(lds + PG8_SA(b, h) + aoff + m * 2048 + k * 1024); } while (0)
; #define PG8_MMA(ai, bj, At, Bt) do { __builtin_amdgcn_s_setprio(1); _Pragma("unroll") for (int m = 0; m < 4; ++m) _Pragma("unroll") for (int n = 0; n < 2; ++n) _Pragma("unroll") for (int k = 0; k < 2; ++k) \
;         acc[ai][bj][m][n] = __builtin_amdgcn_mfma_f32_16x16x32_bf16(Bt[n][k], At[m][k], acc[ai][bj][m][n], 0, 0, 0); __builtin_amdgcn_s_setprio(0); } while (0)
; #define PG8_WAIT_V(n) asm volatile("s_waitcnt vmcnt(" #n ")" ::: "memory")
; #define PG8_WAIT_L(n) asm volatile("s_waitcnt lgkmcnt(" #n ")" ::: "memory")
; #define PG8_BAR __builtin_amdgcn_s_barrier()
; #define PG8_SCHED __builtin_amdgcn_sched_barrier(0)
; template <class Epi, bool ALIGN_EPI>
; __device__ __forceinline__ void gemm_phase(LAS unsigned char* lds, const Gemm g, int G, int cid, const Epi& E) {
;     ...
;         for (int t = 0; t < nt; t += 2) {
;     ...
;             PG8_LDA(At, 1, 1); PG8_STAGE(PG8_SB(1, 0), b3, voffB); PG8_STAGE(PG8_SB(1, 1), b3 + hB, voffB); PG8_STAGE(PG8_SA(1, 0), a3, voffA);
;             PG8_WAIT_V(8); PG8_WAIT_L(0); PG8_BAR; PG8_MMA(1, 0, At, B0); PG8_MMA(1, 1, At, B1); PG8_BAR; PG8_SCHED;
;         }
	s_add_u32 s6, s56, 0x160000
	s_addc_u32 s7, s57, 0
	s_add_i32 s52, s52, s12
	v_lshl_add_u64 v[226:227], s[6:7], 0, v[164:165]
	s_mov_b32 m0, s52
	ds_read_b128 v[180:183], v179 offset:49152
	ds_read_b128 v[184:187], v179 offset:50176
	ds_read_b128 v[188:191], v179 offset:51200
	ds_read_b128 v[206:209], v179 offset:52224
	ds_read_b128 v[210:213], v179 offset:53248
	ds_read_b128 v[214:217], v179 offset:54272
	ds_read_b128 v[218:221], v179 offset:55296
	ds_read_b128 v[222:225], v179 offset:56320
	global_load_lds_dwordx4 v[226:227], off
	s_add_i32 m0, s52, 0x2000
	v_lshl_add_u64 v[226:227], s[6:7], 0, v[168:169]
	s_add_u32 s6, s56, 0x162000
	s_addc_u32 s7, s57, 0
	s_add_i32 s52, s53, s12
	global_load_lds_dwordx4 v[226:227], off
	v_lshl_add_u64 v[226:227], s[6:7], 0, v[164:165]
	s_mov_b32 m0, s52
	v_lshl_add_u64 v[198:199], v[198:199], 0, s[36:37]
	global_load_lds_dwordx4 v[226:227], off
	v_lshl_add_u64 v[226:227], s[6:7], 0, v[168:169]
	s_add_i32 m0, s52, 0x2000
	s_nop 0
	global_load_lds_dwordx4 v[226:227], off
	s_mov_b32 m0, s75
	s_nop 0
	global_load_lds_dwordx4 v[198:199], off
	v_lshl_add_u64 v[198:199], v[200:201], 0, s[36:37]
	s_mov_b32 m0, s76
	s_nop 0
	global_load_lds_dwordx4 v[198:199], off
	s_waitcnt vmcnt(8)
	s_waitcnt lgkmcnt(0)
	s_barrier
	s_setprio 1
	s_waitcnt lgkmcnt(0)
	v_mfma_f32_16x16x32_bf16 v[60:63], v[128:131], v[180:183], v[60:63]
	v_mfma_f32_16x16x32_bf16 v[56:59], v[140:143], v[180:183], v[56:59]
	v_mfma_f32_16x16x32_bf16 v[44:47], v[128:131], v[188:191], v[44:47]
	v_mfma_f32_16x16x32_bf16 v[40:43], v[140:143], v[188:191], v[40:43]
	v_mfma_f32_16x16x32_bf16 v[28:31], v[128:131], v[210:213], v[28:31]
	v_mfma_f32_16x16x32_bf16 v[24:27], v[140:143], v[210:213], v[24:27]
	v_mfma_f32_16x16x32_bf16 v[12:15], v[128:131], v[218:221], v[12:15]
	v_mfma_f32_16x16x32_bf16 v[8:11], v[140:143], v[218:221], v[8:11]
	v_mfma_f32_16x16x32_bf16 v[60:63], v[132:135], v[184:187], v[60:63]
	v_mfma_f32_16x16x32_bf16 v[56:59], v[144:147], v[184:187], v[56:59]
	v_mfma_f32_16x16x32_bf16 v[44:47], v[132:135], v[206:209], v[44:47]
	v_mfma_f32_16x16x32_bf16 v[40:43], v[144:147], v[206:209], v[40:43]
	v_mfma_f32_16x16x32_bf16 v[28:31], v[132:135], v[214:217], v[28:31]
	v_mfma_f32_16x16x32_bf16 v[24:27], v[144:147], v[214:217], v[24:27]
	v_mfma_f32_16x16x32_bf16 v[12:15], v[132:135], v[222:225], v[12:15]
	v_mfma_f32_16x16x32_bf16 v[8:11], v[144:147], v[222:225], v[8:11]
	s_setprio 0
	s_setprio 1
	v_mfma_f32_16x16x32_bf16 v[52:55], v[148:151], v[180:183], v[52:55]
	v_mfma_f32_16x16x32_bf16 v[48:51], v[156:159], v[180:183], v[48:51]
	v_mfma_f32_16x16x32_bf16 v[36:39], v[148:151], v[188:191], v[36:39]
	v_mfma_f32_16x16x32_bf16 v[32:35], v[156:159], v[188:191], v[32:35]
	v_mfma_f32_16x16x32_bf16 v[20:23], v[148:151], v[210:213], v[20:23]
	v_mfma_f32_16x16x32_bf16 v[16:19], v[156:159], v[210:213], v[16:19]
	v_mfma_f32_16x16x32_bf16 v[4:7], v[148:151], v[218:221], v[4:7]
	v_mfma_f32_16x16x32_bf16 v[0:3], v[156:159], v[218:221], v[0:3]
	v_mfma_f32_16x16x32_bf16 v[52:55], v[152:155], v[184:187], v[52:55]
	v_mfma_f32_16x16x32_bf16 v[48:51], v[160:163], v[184:187], v[48:51]
	v_mfma_f32_16x16x32_bf16 v[36:39], v[152:155], v[206:209], v[36:39]
	v_mfma_f32_16x16x32_bf16 v[32:35], v[160:163], v[206:209], v[32:35]
	v_mfma_f32_16x16x32_bf16 v[20:23], v[152:155], v[214:217], v[20:23]
	v_mfma_f32_16x16x32_bf16 v[16:19], v[160:163], v[214:217], v[16:19]
	v_mfma_f32_16x16x32_bf16 v[4:7], v[152:155], v[222:225], v[4:7]
	v_mfma_f32_16x16x32_bf16 v[0:3], v[160:163], v[222:225], v[0:3]
	s_setprio 0
	s_barrier
	s_add_i32 s91, s91, 2
	s_add_u32 s50, s50, 0x2c0000
	s_addc_u32 s51, s51, 0
	s_cmp_gt_u32 s91, 29
	s_mov_b64 s[52:53], s[54:55]
	s_cbranch_scc1 .LBB0_816
